# Q-up epilogue rotary blocks: cos/sin loads 3-deep register pipeline (preload at epilogue start, counted waits) instead of 8 serialized load->vmcnt(0) chains; EpiQ stores back to 8-byte
# baseline (speedup 1.0000x reference)
.LBB0_522:
	s_lshl_b32 s4, s66, 8
	v_mov_b32_e32 v106, v222
	v_mov_b32_e32 v157, v223
	s_add_i32 s4, s4, s41
	s_nop 0
	v_add_u32_e32 v186, s4, v106
	v_ashrrev_i32_e32 v187, 31, v186
	v_lshlrev_b64 v[184:185], 4, v[186:187]
	v_lshl_add_u64 v[106:107], s[90:91], 0, v[184:185]
	global_load_dwordx4 v[106:109], v[106:107], off
	v_add_u32_e32 v200, 16, v186
	v_ashrrev_i32_e32 v201, 31, v200
	v_lshlrev_b64 v[206:207], 4, v[200:201]
	s_mov_b32 s4, 0x3b800000
	v_add_u32_e32 v202, 32, v186
	v_add_u32_e32 v158, 0xb0, v186
	v_ashrrev_i32_e32 v203, 31, v202
	v_add_u32_e32 v196, 48, v186
	v_ashrrev_i32_e32 v159, 31, v158
	v_lshlrev_b64 v[204:205], 4, v[202:203]
	v_ashrrev_i32_e32 v197, 31, v196
	v_add_u32_e32 v190, 0x80, v186
	v_lshlrev_b64 v[160:161], 4, v[158:159]
	v_lshlrev_b64 v[198:199], 4, v[196:197]
	v_ashrrev_i32_e32 v191, 31, v190
	v_add_u32_e32 v182, 0x90, v186
	v_lshlrev_b64 v[194:195], 4, v[190:191]
	v_ashrrev_i32_e32 v183, 31, v182
	v_add_u32_e32 v178, 0xa0, v186
	v_lshlrev_b64 v[188:189], 4, v[182:183]
	v_ashrrev_i32_e32 v179, 31, v178
	v_lshlrev_b64 v[180:181], 4, v[178:179]
	v_lshlrev_b32_e32 v208, 2, v157
	v_ashrrev_i32_e32 v209, 31, v208
	v_lshlrev_b64 v[164:165], 2, v[208:209]
	v_lshl_add_u64 v[162:163], s[78:79], 0, v[164:165]
	v_lshl_add_u64 v[164:165], s[80:81], 0, v[164:165]
	v_lshlrev_b64 v[250:251], 2, v[184:185]
	v_lshl_add_u64 v[214:215], v[164:165], 0, v[250:251]
	v_lshl_add_u64 v[216:217], v[162:163], 0, v[250:251]
	v_mov_b32_e32 v218, 0x2000
	v_mov_b32_e32 v219, 0
	v_lshl_add_u64 v[250:251], v[216:217], 0, v[218:219]
	v_lshl_add_u64 v[218:219], v[214:215], 0, v[218:219]
	global_load_dwordx4 v[226:229], v[214:215], off
	global_load_dwordx4 v[230:233], v[216:217], off
	global_load_dwordx4 v[234:237], v[214:215], off offset:1024
	global_load_dwordx4 v[238:241], v[216:217], off offset:1024
	global_load_dwordx4 v[242:245], v[214:215], off offset:2048
	global_load_dwordx4 v[246:249], v[216:217], off offset:2048
	s_waitcnt vmcnt(0)
	v_mov_b32_e32 v110, v107
	v_mov_b32_e32 v111, v108
	v_mov_b32_e32 v107, v109
	v_pk_add_f32 v[110:111], v[110:111], v[106:107]
	v_lshl_add_u64 v[106:107], s[90:91], 0, v[206:207]
	global_load_dwordx4 v[106:109], v[106:107], off
	s_waitcnt vmcnt(0)
	v_mov_b32_e32 v112, v107
	v_mov_b32_e32 v113, v108
	v_mov_b32_e32 v107, v109
	v_pk_add_f32 v[106:107], v[112:113], v[106:107]
	v_mov_b32_e32 v109, v110
	v_mov_b32_e32 v108, v106
	v_mov_b32_e32 v110, v107
	v_pk_add_f32 v[106:107], v[108:109], v[110:111]
	v_lshl_add_u64 v[110:111], s[90:91], 0, v[160:161]
	v_pk_fma_f32 v[192:193], v[106:107], s[4:5], v[166:167] op_sel_hi:[1,0,0]
	global_load_dwordx4 v[110:113], v[110:111], off
	v_mul_f32_e32 v106, 0x4b800000, v193
	v_cmp_gt_f32_e64 s[4:5], s29, v193
	v_cmp_gt_f32_e32 vcc, s29, v192
	s_nop 0
	v_cndmask_b32_e64 v106, v193, v106, s[4:5]
	v_rsq_f32_e32 v106, v106
	s_nop 0
	v_mul_f32_e32 v107, 0x45800000, v106
	v_cndmask_b32_e64 v106, v106, v107, s[4:5]
	v_mul_f32_e32 v156, 0x3e16c740, v106
	v_lshl_add_u64 v[106:107], s[90:91], 0, v[204:205]
	global_load_dwordx4 v[138:141], v[106:107], off
	v_lshl_add_u64 v[106:107], s[90:91], 0, v[198:199]
	global_load_dwordx4 v[142:145], v[106:107], off
	v_lshl_add_u64 v[106:107], s[90:91], 0, v[194:195]
	global_load_dwordx4 v[130:133], v[106:107], off
	v_lshl_add_u64 v[106:107], s[90:91], 0, v[188:189]
	global_load_dwordx4 v[134:137], v[106:107], off
	v_lshl_add_u64 v[106:107], s[90:91], 0, v[180:181]
	global_load_dwordx4 v[106:109], v[106:107], off
	s_lshl_b32 s4, s65, 8
	s_or_b32 s4, s4, s62
	s_ashr_i32 s15, s4, 5
	s_mul_hi_i32 s5, s15, 0x55555556
	s_lshr_b32 s6, s5, 31
	s_add_i32 s5, s5, s6
	s_mul_i32 s5, s5, 3
	s_sub_i32 s5, s15, s5
	s_cmp_eq_u32 s5, 2
	v_pk_mul_f32 v[210:211], v[152:153], v[156:157] op_sel_hi:[1,0]
	v_lshlrev_b64 v[152:153], 2, v[184:185]
	s_cselect_b64 s[58:59], -1, 0
	s_cmp_lg_u32 s5, 2
	v_pk_mul_f32 v[148:149], v[148:149], v[156:157] op_sel_hi:[1,0]
	v_pk_mul_f32 v[146:147], v[146:147], v[156:157] op_sel_hi:[1,0]
	v_pk_mul_f32 v[212:213], v[150:151], v[156:157] op_sel_hi:[1,0]
	v_lshl_add_u64 v[150:151], v[162:163], 0, v[152:153]
	v_lshl_add_u64 v[184:185], v[164:165], 0, v[152:153]
	s_cbranch_scc1 .LBB0_524
	v_pk_mul_f32 v[152:153], v[210:211], v[228:229]
	v_pk_mul_f32 v[176:177], v[212:213], v[226:227]
	v_pk_mul_f32 v[228:229], v[148:149], v[228:229]
	v_pk_mul_f32 v[226:227], v[146:147], v[226:227]
	v_pk_fma_f32 v[148:149], v[148:149], v[232:233], v[152:153] neg_lo:[0,0,1] neg_hi:[0,0,1]
	v_pk_fma_f32 v[146:147], v[146:147], v[230:231], v[176:177] neg_lo:[0,0,1] neg_hi:[0,0,1]
	v_pk_fma_f32 v[210:211], v[210:211], v[232:233], v[228:229]
	v_pk_fma_f32 v[212:213], v[212:213], v[230:231], v[226:227]
	global_load_dwordx4 v[226:229], v[214:215], off offset:3072
	global_load_dwordx4 v[230:233], v[216:217], off offset:3072
.LBB0_524:
	v_mul_f32_e32 v152, 0x4b800000, v192
	v_cndmask_b32_e32 v152, v192, v152, vcc
	v_rsq_f32_e32 v152, v152
	v_readlane_b32 s6, v253, 50
	v_readlane_b32 s7, v253, 51
	s_ashr_i32 s5, s4, 31
	v_mul_f32_e32 v153, 0x45800000, v152
	v_lshl_add_u64 v[168:169], v[208:209], 1, s[6:7]
	v_lshl_add_u64 v[192:193], s[4:5], 1, v[168:169]
	v_cndmask_b32_e32 v152, v152, v153, vcc
	v_mad_i64_i32 v[186:187], s[4:5], v186, s92, v[192:193]
	v_cvt_pk_bf16_f32 v146, v146, v147
	v_cvt_pk_bf16_f32 v147, v148, v149
	v_mul_f32_e32 v152, 0x3e16c740, v152
	global_store_dwordx2 v[186:187], v[146:147], off
	v_cvt_pk_bf16_f32 v146, v212, v213
	v_cvt_pk_bf16_f32 v147, v210, v211
	global_store_dwordx2 v[186:187], v[146:147], off offset:32
	v_pk_mul_f32 v[146:147], v[124:125], v[152:153] op_sel_hi:[1,0]
	v_pk_mul_f32 v[148:149], v[122:123], v[152:153] op_sel_hi:[1,0]
	v_cndmask_b32_e64 v122, 0, 1, s[58:59]
	v_lshlrev_b64 v[124:125], 2, v[206:207]
	v_pk_mul_f32 v[128:129], v[128:129], v[152:153] op_sel_hi:[1,0]
	v_pk_mul_f32 v[126:127], v[126:127], v[152:153] op_sel_hi:[1,0]
	v_cmp_ne_u32_e64 s[6:7], 1, v122
	s_andn2_b64 vcc, exec, s[58:59]
	v_lshl_add_u64 v[122:123], v[162:163], 0, v[124:125]
	v_lshl_add_u64 v[124:125], v[164:165], 0, v[124:125]
	s_cbranch_vccnz .LBB0_526
	v_pk_mul_f32 v[176:177], v[146:147], v[236:237]
	v_pk_mul_f32 v[206:207], v[148:149], v[234:235]
	v_pk_mul_f32 v[236:237], v[128:129], v[236:237]
	v_pk_mul_f32 v[234:235], v[126:127], v[234:235]
	v_pk_fma_f32 v[128:129], v[128:129], v[240:241], v[176:177] neg_lo:[0,0,1] neg_hi:[0,0,1]
	v_pk_fma_f32 v[126:127], v[126:127], v[238:239], v[206:207] neg_lo:[0,0,1] neg_hi:[0,0,1]
	v_pk_fma_f32 v[146:147], v[146:147], v[240:241], v[236:237]
	v_pk_fma_f32 v[148:149], v[148:149], v[238:239], v[234:235]
	global_load_dwordx4 v[234:237], v[218:219], off
	global_load_dwordx4 v[238:241], v[250:251], off
.LBB0_526:
	s_waitcnt vmcnt(6)
	v_mov_b32_e32 v168, v139
	v_mov_b32_e32 v169, v140
	v_mov_b32_e32 v139, v141
	s_waitcnt vmcnt(5)
	v_mov_b32_e32 v140, v143
	v_mov_b32_e32 v141, v144
	v_mov_b32_e32 v143, v145
	v_pk_add_f32 v[138:139], v[168:169], v[138:139]
	v_pk_add_f32 v[140:141], v[140:141], v[142:143]
	v_mov_b32_e32 v143, v138
	v_mov_b32_e32 v142, v140
	v_mov_b32_e32 v138, v141
	v_pk_add_f32 v[138:139], v[142:143], v[138:139]
	s_mov_b32 s4, 0x3b800000
	v_pk_fma_f32 v[206:207], v[138:139], s[4:5], v[166:167] op_sel_hi:[1,0,0]
	v_mad_i64_i32 v[140:141], s[26:27], v200, s92, v[192:193]
	v_mul_f32_e32 v138, 0x4b800000, v207
	v_cmp_gt_f32_e32 vcc, s29, v207
	v_cvt_pk_bf16_f32 v126, v126, v127
	v_cvt_pk_bf16_f32 v127, v128, v129
	v_cndmask_b32_e32 v138, v207, v138, vcc
	v_rsq_f32_e32 v138, v138
	global_store_dwordx2 v[140:141], v[126:127], off
	v_cvt_pk_bf16_f32 v126, v148, v149
	v_cvt_pk_bf16_f32 v127, v146, v147
	v_mul_f32_e32 v139, 0x45800000, v138
	v_cndmask_b32_e32 v138, v138, v139, vcc
	global_store_dwordx2 v[140:141], v[126:127], off offset:32
	v_mul_f32_e32 v138, 0x3e16c740, v138
	v_pk_mul_f32 v[144:145], v[114:115], v[138:139] op_sel_hi:[1,0]
	v_lshlrev_b64 v[114:115], 2, v[204:205]
	v_cmp_gt_f32_e64 s[4:5], s29, v206
	v_pk_mul_f32 v[120:121], v[120:121], v[138:139] op_sel_hi:[1,0]
	v_pk_mul_f32 v[118:119], v[118:119], v[138:139] op_sel_hi:[1,0]
	v_pk_mul_f32 v[142:143], v[116:117], v[138:139] op_sel_hi:[1,0]
	s_and_b64 vcc, exec, s[6:7]
	v_lshl_add_u64 v[116:117], v[162:163], 0, v[114:115]
	v_lshl_add_u64 v[126:127], v[164:165], 0, v[114:115]
	s_cbranch_vccnz .LBB0_528
	v_pk_mul_f32 v[114:115], v[142:143], v[244:245]
	v_pk_mul_f32 v[128:129], v[144:145], v[242:243]
	v_pk_mul_f32 v[244:245], v[120:121], v[244:245]
	v_pk_mul_f32 v[242:243], v[118:119], v[242:243]
	v_pk_fma_f32 v[120:121], v[120:121], v[248:249], v[114:115] neg_lo:[0,0,1] neg_hi:[0,0,1]
	v_pk_fma_f32 v[118:119], v[118:119], v[246:247], v[128:129] neg_lo:[0,0,1] neg_hi:[0,0,1]
	v_pk_fma_f32 v[142:143], v[142:143], v[248:249], v[244:245]
	v_pk_fma_f32 v[144:145], v[144:145], v[246:247], v[242:243]
	global_load_dwordx4 v[242:245], v[218:219], off offset:1024
	global_load_dwordx4 v[246:249], v[250:251], off offset:1024
.LBB0_528:
	v_mul_f32_e32 v114, 0x4b800000, v206
	v_cndmask_b32_e64 v114, v206, v114, s[4:5]
	v_rsq_f32_e32 v114, v114
	v_cvt_pk_bf16_f32 v118, v118, v119
	v_cvt_pk_bf16_f32 v119, v120, v121
	s_and_b64 vcc, exec, s[6:7]
	v_mul_f32_e32 v115, 0x45800000, v114
	v_cndmask_b32_e64 v114, v114, v115, s[4:5]
	v_mul_f32_e32 v114, 0x3e16c740, v114
	v_mad_i64_i32 v[128:129], s[4:5], v202, s92, v[192:193]
	global_store_dwordx2 v[128:129], v[118:119], off
	v_cvt_pk_bf16_f32 v119, v142, v143
	v_pk_mul_f32 v[142:143], v[100:101], v[114:115] op_sel_hi:[1,0]
	v_lshlrev_b64 v[100:101], 2, v[198:199]
	v_cvt_pk_bf16_f32 v118, v144, v145
	v_pk_mul_f32 v[104:105], v[104:105], v[114:115] op_sel_hi:[1,0]
	v_pk_mul_f32 v[102:103], v[102:103], v[114:115] op_sel_hi:[1,0]
	v_pk_mul_f32 v[144:145], v[98:99], v[114:115] op_sel_hi:[1,0]
	v_lshl_add_u64 v[98:99], v[162:163], 0, v[100:101]
	v_lshl_add_u64 v[100:101], v[164:165], 0, v[100:101]
	global_store_dwordx2 v[128:129], v[118:119], off offset:32
	s_cbranch_vccnz .LBB0_530
	s_waitcnt vmcnt(10)
	v_pk_mul_f32 v[168:169], v[142:143], v[228:229]
	v_pk_mul_f32 v[170:171], v[144:145], v[226:227]
	v_pk_mul_f32 v[228:229], v[104:105], v[228:229]
	v_pk_mul_f32 v[226:227], v[102:103], v[226:227]
	v_pk_fma_f32 v[104:105], v[104:105], v[232:233], v[168:169] neg_lo:[0,0,1] neg_hi:[0,0,1]
	v_pk_fma_f32 v[102:103], v[102:103], v[230:231], v[170:171] neg_lo:[0,0,1] neg_hi:[0,0,1]
	v_pk_fma_f32 v[142:143], v[142:143], v[232:233], v[228:229]
	v_pk_fma_f32 v[144:145], v[144:145], v[230:231], v[226:227]
	global_load_dwordx4 v[226:229], v[218:219], off offset:2048
	global_load_dwordx4 v[230:233], v[250:251], off offset:2048
.LBB0_530:
	s_waitcnt vmcnt(8)
	v_mov_b32_e32 v118, v131
	v_mov_b32_e32 v119, v132
	v_mov_b32_e32 v131, v133
	s_waitcnt vmcnt(7)
	v_mov_b32_e32 v120, v135
	v_mov_b32_e32 v121, v136
	v_mov_b32_e32 v135, v137
	v_pk_add_f32 v[118:119], v[118:119], v[130:131]
	v_pk_add_f32 v[120:121], v[120:121], v[134:135]
	v_mov_b32_e32 v131, v118
	v_mov_b32_e32 v130, v120
	v_mov_b32_e32 v118, v121
	v_pk_add_f32 v[118:119], v[130:131], v[118:119]
	s_mov_b32 s4, 0x3b800000
	v_pk_fma_f32 v[134:135], v[118:119], s[4:5], v[166:167] op_sel_hi:[1,0,0]
	v_mad_i64_i32 v[120:121], s[26:27], v196, s92, v[192:193]
	v_mul_f32_e32 v115, 0x4b800000, v135
	v_cmp_gt_f32_e32 vcc, s29, v135
	v_cvt_pk_bf16_f32 v102, v102, v103
	v_cvt_pk_bf16_f32 v103, v104, v105
	v_cndmask_b32_e32 v115, v135, v115, vcc
	v_rsq_f32_e32 v115, v115
	global_store_dwordx2 v[120:121], v[102:103], off
	v_cvt_pk_bf16_f32 v102, v144, v145
	v_cvt_pk_bf16_f32 v103, v142, v143
	v_mul_f32_e32 v118, 0x45800000, v115
	v_cndmask_b32_e32 v115, v115, v118, vcc
	global_store_dwordx2 v[120:121], v[102:103], off offset:32
	v_mul_f32_e32 v118, 0x3e16c740, v115
	v_pk_mul_f32 v[132:133], v[90:91], v[118:119] op_sel_hi:[1,0]
	v_lshlrev_b64 v[90:91], 2, v[194:195]
	v_cmp_gt_f32_e64 s[4:5], s29, v134
	v_pk_mul_f32 v[96:97], v[96:97], v[118:119] op_sel_hi:[1,0]
	v_pk_mul_f32 v[94:95], v[94:95], v[118:119] op_sel_hi:[1,0]
	v_pk_mul_f32 v[130:131], v[92:93], v[118:119] op_sel_hi:[1,0]
	s_and_b64 vcc, exec, s[6:7]
	v_lshl_add_u64 v[92:93], v[162:163], 0, v[90:91]
	v_lshl_add_u64 v[102:103], v[164:165], 0, v[90:91]
	s_cbranch_vccnz .LBB0_532
	s_waitcnt vmcnt(10)
	v_pk_mul_f32 v[90:91], v[130:131], v[236:237]
	v_pk_mul_f32 v[104:105], v[132:133], v[234:235]
	v_pk_mul_f32 v[136:137], v[96:97], v[236:237]
	v_pk_mul_f32 v[234:235], v[94:95], v[234:235]
	v_pk_fma_f32 v[96:97], v[96:97], v[240:241], v[90:91] neg_lo:[0,0,1] neg_hi:[0,0,1]
	v_pk_fma_f32 v[94:95], v[94:95], v[238:239], v[104:105] neg_lo:[0,0,1] neg_hi:[0,0,1]
	v_pk_fma_f32 v[130:131], v[130:131], v[240:241], v[136:137]
	v_pk_fma_f32 v[132:133], v[132:133], v[238:239], v[234:235]
	global_load_dwordx4 v[234:237], v[218:219], off offset:3072
	global_load_dwordx4 v[238:241], v[250:251], off offset:3072
.LBB0_532:
	v_mul_f32_e32 v90, 0x4b800000, v134
	v_cndmask_b32_e64 v90, v134, v90, s[4:5]
	v_rsq_f32_e32 v90, v90
	v_cvt_pk_bf16_f32 v94, v94, v95
	v_cvt_pk_bf16_f32 v95, v96, v97
	s_and_b64 vcc, exec, s[6:7]
	v_mul_f32_e32 v91, 0x45800000, v90
	v_cndmask_b32_e64 v90, v90, v91, s[4:5]
	v_mul_f32_e32 v90, 0x3e16c740, v90
	v_mad_i64_i32 v[104:105], s[4:5], v190, s92, v[192:193]
	global_store_dwordx2 v[104:105], v[94:95], off
	v_cvt_pk_bf16_f32 v95, v130, v131
	v_pk_mul_f32 v[130:131], v[84:85], v[90:91] op_sel_hi:[1,0]
	v_lshlrev_b64 v[84:85], 2, v[188:189]
	v_cvt_pk_bf16_f32 v94, v132, v133
	v_pk_mul_f32 v[88:89], v[88:89], v[90:91] op_sel_hi:[1,0]
	v_pk_mul_f32 v[86:87], v[86:87], v[90:91] op_sel_hi:[1,0]
	v_pk_mul_f32 v[132:133], v[82:83], v[90:91] op_sel_hi:[1,0]
	v_lshl_add_u64 v[82:83], v[162:163], 0, v[84:85]
	v_lshl_add_u64 v[84:85], v[164:165], 0, v[84:85]
	global_store_dwordx2 v[104:105], v[94:95], off offset:32
	s_cbranch_vccnz .LBB0_534
	s_waitcnt vmcnt(10)
	v_pk_mul_f32 v[142:143], v[130:131], v[244:245]
	v_pk_mul_f32 v[144:145], v[132:133], v[242:243]
	v_pk_mul_f32 v[244:245], v[88:89], v[244:245]
	v_pk_mul_f32 v[242:243], v[86:87], v[242:243]
	v_pk_fma_f32 v[88:89], v[88:89], v[248:249], v[142:143] neg_lo:[0,0,1] neg_hi:[0,0,1]
	v_pk_fma_f32 v[86:87], v[86:87], v[246:247], v[144:145] neg_lo:[0,0,1] neg_hi:[0,0,1]
	v_pk_fma_f32 v[130:131], v[130:131], v[248:249], v[244:245]
	v_pk_fma_f32 v[132:133], v[132:133], v[246:247], v[242:243]
.LBB0_534:
	s_waitcnt vmcnt(10)
	v_mov_b32_e32 v94, v107
	v_mov_b32_e32 v95, v108
	v_mov_b32_e32 v107, v109
	v_mov_b32_e32 v96, v111
	v_mov_b32_e32 v97, v112
	v_mov_b32_e32 v111, v113
	v_pk_add_f32 v[94:95], v[94:95], v[106:107]
	v_pk_add_f32 v[96:97], v[96:97], v[110:111]
	v_mov_b32_e32 v107, v94
	v_mov_b32_e32 v106, v96
	v_mov_b32_e32 v94, v97
	v_pk_add_f32 v[94:95], v[106:107], v[94:95]
	s_mov_b32 s4, 0x3b800000
	v_pk_fma_f32 v[110:111], v[94:95], s[4:5], v[166:167] op_sel_hi:[1,0,0]
	v_mad_i64_i32 v[96:97], s[26:27], v182, s92, v[192:193]
	v_mul_f32_e32 v91, 0x4b800000, v111
	v_cmp_gt_f32_e32 vcc, s29, v111
	v_cvt_pk_bf16_f32 v86, v86, v87
	v_cvt_pk_bf16_f32 v87, v88, v89
	v_cndmask_b32_e32 v91, v111, v91, vcc
	v_rsq_f32_e32 v91, v91
	global_store_dwordx2 v[96:97], v[86:87], off
	v_cvt_pk_bf16_f32 v86, v132, v133
	v_cvt_pk_bf16_f32 v87, v130, v131
	v_mul_f32_e32 v94, 0x45800000, v91
	v_cndmask_b32_e32 v91, v91, v94, vcc
	global_store_dwordx2 v[96:97], v[86:87], off offset:32
	v_mul_f32_e32 v94, 0x3e16c740, v91
	v_pk_mul_f32 v[108:109], v[74:75], v[94:95] op_sel_hi:[1,0]
	v_lshlrev_b64 v[74:75], 2, v[180:181]
	v_cmp_gt_f32_e64 s[4:5], s29, v110
	v_pk_mul_f32 v[80:81], v[80:81], v[94:95] op_sel_hi:[1,0]
	v_pk_mul_f32 v[78:79], v[78:79], v[94:95] op_sel_hi:[1,0]
	v_pk_mul_f32 v[106:107], v[76:77], v[94:95] op_sel_hi:[1,0]
	s_and_b64 vcc, exec, s[6:7]
	v_lshl_add_u64 v[76:77], v[162:163], 0, v[74:75]
	v_lshl_add_u64 v[86:87], v[164:165], 0, v[74:75]
	s_cbranch_vccnz .LBB0_536
	s_waitcnt vmcnt(8)
	v_pk_mul_f32 v[74:75], v[106:107], v[228:229]
	v_pk_mul_f32 v[88:89], v[108:109], v[226:227]
	v_pk_mul_f32 v[112:113], v[80:81], v[228:229]
	v_pk_mul_f32 v[226:227], v[78:79], v[226:227]
	v_pk_fma_f32 v[80:81], v[80:81], v[232:233], v[74:75] neg_lo:[0,0,1] neg_hi:[0,0,1]
	v_pk_fma_f32 v[78:79], v[78:79], v[230:231], v[88:89] neg_lo:[0,0,1] neg_hi:[0,0,1]
	v_pk_fma_f32 v[106:107], v[106:107], v[232:233], v[112:113]
	v_pk_fma_f32 v[108:109], v[108:109], v[230:231], v[226:227]
.LBB0_536:
	v_mul_f32_e32 v74, 0x4b800000, v110
	v_cndmask_b32_e64 v74, v110, v74, s[4:5]
	v_rsq_f32_e32 v74, v74
	v_cvt_pk_bf16_f32 v78, v78, v79
	v_cvt_pk_bf16_f32 v79, v80, v81
	s_and_b64 vcc, exec, s[6:7]
	v_mul_f32_e32 v75, 0x45800000, v74
	v_cndmask_b32_e64 v74, v74, v75, s[4:5]
	v_mul_f32_e32 v74, 0x3e16c740, v74
	v_mad_i64_i32 v[88:89], s[4:5], v178, s92, v[192:193]
	global_store_dwordx2 v[88:89], v[78:79], off
	v_cvt_pk_bf16_f32 v78, v108, v109
	v_cvt_pk_bf16_f32 v79, v106, v107
	v_pk_mul_f32 v[106:107], v[66:67], v[74:75] op_sel_hi:[1,0]
	v_lshlrev_b64 v[66:67], 2, v[160:161]
	global_store_dwordx2 v[88:89], v[78:79], off offset:32
	v_pk_mul_f32 v[72:73], v[72:73], v[74:75] op_sel_hi:[1,0]
	v_pk_mul_f32 v[70:71], v[70:71], v[74:75] op_sel_hi:[1,0]
	v_pk_mul_f32 v[80:81], v[68:69], v[74:75] op_sel_hi:[1,0]
	v_lshl_add_u64 v[68:69], v[162:163], 0, v[66:67]
	v_lshl_add_u64 v[78:79], v[164:165], 0, v[66:67]
	s_cbranch_vccnz .LBB0_538
	s_waitcnt vmcnt(6)
	v_pk_mul_f32 v[66:67], v[80:81], v[236:237]
	v_pk_mul_f32 v[112:113], v[106:107], v[234:235]
	v_pk_mul_f32 v[236:237], v[72:73], v[236:237]
	v_pk_mul_f32 v[234:235], v[70:71], v[234:235]
	v_pk_fma_f32 v[72:73], v[72:73], v[240:241], v[66:67] neg_lo:[0,0,1] neg_hi:[0,0,1]
	v_pk_fma_f32 v[70:71], v[70:71], v[238:239], v[112:113] neg_lo:[0,0,1] neg_hi:[0,0,1]
	v_pk_fma_f32 v[80:81], v[80:81], v[240:241], v[236:237]
	v_pk_fma_f32 v[106:107], v[106:107], v[238:239], v[234:235]
.LBB0_538:
	v_mad_i64_i32 v[66:67], s[4:5], v158, s92, v[192:193]
	s_or_b32 s4, s15, 4
	s_mul_hi_i32 s5, s4, 0x55555556
	v_cvt_pk_bf16_f32 v70, v70, v71
	v_cvt_pk_bf16_f32 v71, v72, v73
	s_lshr_b32 s6, s5, 31
	global_store_dwordx2 v[66:67], v[70:71], off
	v_cvt_pk_bf16_f32 v70, v106, v107
	v_cvt_pk_bf16_f32 v71, v80, v81
	s_add_i32 s5, s5, s6
	global_store_dwordx2 v[66:67], v[70:71], off offset:32
	s_mul_i32 s5, s5, 3
	s_sub_i32 s4, s4, s5
	v_mov_b32_e32 v157, v156
	s_cmp_eq_u32 s4, 2
	v_mov_b32_e32 v70, v156
	v_mov_b32_e32 v71, v156
	s_cselect_b64 s[6:7], -1, 0
	s_cmp_lg_u32 s4, 2
	v_pk_mul_f32 v[64:65], v[64:65], v[70:71]
	v_pk_mul_f32 v[62:63], v[62:63], v[156:157]
	v_pk_mul_f32 v[60:61], v[60:61], v[70:71]
	v_pk_mul_f32 v[58:59], v[58:59], v[156:157]
	s_cbranch_scc1 .LBB0_540
	v_pk_mul_f32 v[80:81], v[60:61], v[228:229]
	v_pk_mul_f32 v[110:111], v[58:59], v[226:227]
	v_pk_mul_f32 v[228:229], v[64:65], v[228:229]
	v_pk_mul_f32 v[226:227], v[62:63], v[226:227]
	v_pk_fma_f32 v[64:65], v[64:65], v[232:233], v[80:81] neg_lo:[0,0,1] neg_hi:[0,0,1]
	v_pk_fma_f32 v[62:63], v[62:63], v[230:231], v[110:111] neg_lo:[0,0,1] neg_hi:[0,0,1]
	v_pk_fma_f32 v[60:61], v[60:61], v[232:233], v[228:229]
	v_pk_fma_f32 v[58:59], v[58:59], v[230:231], v[226:227]
	global_load_dwordx4 v[226:229], v[214:215], off offset:3072
	global_load_dwordx4 v[230:233], v[216:217], off offset:3072
.LBB0_540:
	s_nop 0
	v_cvt_pk_bf16_f32 v58, v58, v59
	v_cvt_pk_bf16_f32 v59, v60, v61
	global_store_dwordx2 v[186:187], v[58:59], off offset:288
	v_mov_b32_e32 v58, v152
	v_mov_b32_e32 v59, v152
	v_mov_b32_e32 v153, v152
	v_pk_mul_f32 v[56:57], v[56:57], v[58:59]
	v_pk_mul_f32 v[52:53], v[52:53], v[58:59]
	v_cndmask_b32_e64 v58, 0, 1, s[6:7]
	v_cvt_pk_bf16_f32 v62, v62, v63
	v_cvt_pk_bf16_f32 v63, v64, v65
	v_pk_mul_f32 v[54:55], v[54:55], v[152:153]
	v_cmp_ne_u32_e64 s[4:5], 1, v58
	s_andn2_b64 vcc, exec, s[6:7]
	v_pk_mul_f32 v[50:51], v[50:51], v[152:153]
	global_store_dwordx2 v[186:187], v[62:63], off offset:256
	s_cbranch_vccnz .LBB0_542
	v_pk_mul_f32 v[70:71], v[52:53], v[236:237]
	v_pk_mul_f32 v[72:73], v[50:51], v[234:235]
	v_pk_mul_f32 v[236:237], v[56:57], v[236:237]
	v_pk_mul_f32 v[234:235], v[54:55], v[234:235]
	v_pk_fma_f32 v[56:57], v[56:57], v[240:241], v[70:71] neg_lo:[0,0,1] neg_hi:[0,0,1]
	v_pk_fma_f32 v[54:55], v[54:55], v[238:239], v[72:73] neg_lo:[0,0,1] neg_hi:[0,0,1]
	v_pk_fma_f32 v[52:53], v[52:53], v[240:241], v[236:237]
	v_pk_fma_f32 v[50:51], v[50:51], v[238:239], v[234:235]
	global_load_dwordx4 v[234:237], v[218:219], off
	global_load_dwordx4 v[238:241], v[250:251], off
.LBB0_542:
	v_cvt_pk_bf16_f32 v54, v54, v55
	v_cvt_pk_bf16_f32 v55, v56, v57
	v_cvt_pk_bf16_f32 v50, v50, v51
	v_cvt_pk_bf16_f32 v51, v52, v53
	global_store_dwordx2 v[140:141], v[54:55], off offset:256
	global_store_dwordx2 v[140:141], v[50:51], off offset:288
	v_mov_b32_e32 v139, v138
	v_mov_b32_e32 v50, v138
	v_mov_b32_e32 v51, v138
	v_pk_mul_f32 v[48:49], v[48:49], v[50:51]
	v_pk_mul_f32 v[46:47], v[46:47], v[138:139]
	v_pk_mul_f32 v[44:45], v[44:45], v[50:51]
	s_and_b64 vcc, exec, s[4:5]
	v_pk_mul_f32 v[42:43], v[42:43], v[138:139]
	s_cbranch_vccnz .LBB0_544
	v_pk_mul_f32 v[58:59], v[44:45], v[244:245]
	v_pk_mul_f32 v[60:61], v[42:43], v[242:243]
	v_pk_mul_f32 v[244:245], v[48:49], v[244:245]
	v_pk_mul_f32 v[242:243], v[46:47], v[242:243]
	v_pk_fma_f32 v[48:49], v[48:49], v[248:249], v[58:59] neg_lo:[0,0,1] neg_hi:[0,0,1]
	v_pk_fma_f32 v[46:47], v[46:47], v[246:247], v[60:61] neg_lo:[0,0,1] neg_hi:[0,0,1]
	v_pk_fma_f32 v[44:45], v[44:45], v[248:249], v[244:245]
	v_pk_fma_f32 v[42:43], v[42:43], v[246:247], v[242:243]
	global_load_dwordx4 v[242:245], v[218:219], off offset:1024
	global_load_dwordx4 v[246:249], v[250:251], off offset:1024
.LBB0_544:
	s_nop 0
	v_cvt_pk_bf16_f32 v42, v42, v43
	v_cvt_pk_bf16_f32 v43, v44, v45
	v_mov_b32_e32 v115, v114
	global_store_dwordx2 v[128:129], v[42:43], off offset:288
	v_mov_b32_e32 v42, v114
	v_mov_b32_e32 v43, v114
	v_cvt_pk_bf16_f32 v46, v46, v47
	v_cvt_pk_bf16_f32 v47, v48, v49
	v_pk_mul_f32 v[40:41], v[40:41], v[42:43]
	v_pk_mul_f32 v[38:39], v[38:39], v[114:115]
	v_pk_mul_f32 v[36:37], v[36:37], v[42:43]
	s_and_b64 vcc, exec, s[4:5]
	v_pk_mul_f32 v[34:35], v[34:35], v[114:115]
	global_store_dwordx2 v[128:129], v[46:47], off offset:256
	s_cbranch_vccnz .LBB0_546
	s_waitcnt vmcnt(10)
	v_pk_mul_f32 v[50:51], v[36:37], v[228:229]
	v_pk_mul_f32 v[52:53], v[34:35], v[226:227]
	v_pk_mul_f32 v[228:229], v[40:41], v[228:229]
	v_pk_mul_f32 v[226:227], v[38:39], v[226:227]
	v_pk_fma_f32 v[40:41], v[40:41], v[232:233], v[50:51] neg_lo:[0,0,1] neg_hi:[0,0,1]
	v_pk_fma_f32 v[38:39], v[38:39], v[230:231], v[52:53] neg_lo:[0,0,1] neg_hi:[0,0,1]
	v_pk_fma_f32 v[36:37], v[36:37], v[232:233], v[228:229]
	v_pk_fma_f32 v[34:35], v[34:35], v[230:231], v[226:227]
	global_load_dwordx4 v[226:229], v[218:219], off offset:2048
	global_load_dwordx4 v[230:233], v[250:251], off offset:2048
.LBB0_546:
	v_cvt_pk_bf16_f32 v38, v38, v39
	v_cvt_pk_bf16_f32 v39, v40, v41
	v_cvt_pk_bf16_f32 v34, v34, v35
	v_cvt_pk_bf16_f32 v35, v36, v37
	global_store_dwordx2 v[120:121], v[38:39], off offset:256
	global_store_dwordx2 v[120:121], v[34:35], off offset:288
	v_mov_b32_e32 v119, v118
	v_mov_b32_e32 v34, v118
	v_mov_b32_e32 v35, v118
	v_pk_mul_f32 v[32:33], v[32:33], v[34:35]
	v_pk_mul_f32 v[30:31], v[30:31], v[118:119]
	v_pk_mul_f32 v[28:29], v[28:29], v[34:35]
	s_and_b64 vcc, exec, s[4:5]
	v_pk_mul_f32 v[26:27], v[26:27], v[118:119]
	s_cbranch_vccnz .LBB0_548
	s_waitcnt vmcnt(10)
	v_pk_mul_f32 v[42:43], v[28:29], v[236:237]
	v_pk_mul_f32 v[44:45], v[26:27], v[234:235]
	v_pk_mul_f32 v[236:237], v[32:33], v[236:237]
	v_pk_mul_f32 v[234:235], v[30:31], v[234:235]
	v_pk_fma_f32 v[32:33], v[32:33], v[240:241], v[42:43] neg_lo:[0,0,1] neg_hi:[0,0,1]
	v_pk_fma_f32 v[30:31], v[30:31], v[238:239], v[44:45] neg_lo:[0,0,1] neg_hi:[0,0,1]
	v_pk_fma_f32 v[28:29], v[28:29], v[240:241], v[236:237]
	v_pk_fma_f32 v[26:27], v[26:27], v[238:239], v[234:235]
	global_load_dwordx4 v[234:237], v[218:219], off offset:3072
	global_load_dwordx4 v[238:241], v[250:251], off offset:3072
.LBB0_548:
	s_nop 0
	v_cvt_pk_bf16_f32 v26, v26, v27
	v_cvt_pk_bf16_f32 v27, v28, v29
	v_mov_b32_e32 v91, v90
	global_store_dwordx2 v[104:105], v[26:27], off offset:288
	v_mov_b32_e32 v26, v90
	v_mov_b32_e32 v27, v90
	v_cvt_pk_bf16_f32 v30, v30, v31
	v_cvt_pk_bf16_f32 v31, v32, v33
	v_pk_mul_f32 v[24:25], v[24:25], v[26:27]
	v_pk_mul_f32 v[22:23], v[22:23], v[90:91]
	v_pk_mul_f32 v[20:21], v[20:21], v[26:27]
	s_and_b64 vcc, exec, s[4:5]
	v_pk_mul_f32 v[18:19], v[18:19], v[90:91]
	global_store_dwordx2 v[104:105], v[30:31], off offset:256
	s_cbranch_vccnz .LBB0_550
	s_waitcnt vmcnt(10)
	v_pk_mul_f32 v[34:35], v[20:21], v[244:245]
	v_pk_mul_f32 v[36:37], v[18:19], v[242:243]
	v_pk_mul_f32 v[244:245], v[24:25], v[244:245]
	v_pk_mul_f32 v[242:243], v[22:23], v[242:243]
	v_pk_fma_f32 v[24:25], v[24:25], v[248:249], v[34:35] neg_lo:[0,0,1] neg_hi:[0,0,1]
	v_pk_fma_f32 v[22:23], v[22:23], v[246:247], v[36:37] neg_lo:[0,0,1] neg_hi:[0,0,1]
	v_pk_fma_f32 v[20:21], v[20:21], v[248:249], v[244:245]
	v_pk_fma_f32 v[18:19], v[18:19], v[246:247], v[242:243]
.LBB0_550:
	v_cvt_pk_bf16_f32 v22, v22, v23
	v_cvt_pk_bf16_f32 v23, v24, v25
	v_cvt_pk_bf16_f32 v18, v18, v19
	v_cvt_pk_bf16_f32 v19, v20, v21
	global_store_dwordx2 v[96:97], v[22:23], off offset:256
	global_store_dwordx2 v[96:97], v[18:19], off offset:288
	v_mov_b32_e32 v95, v94
	v_mov_b32_e32 v18, v94
	v_mov_b32_e32 v19, v94
	v_pk_mul_f32 v[16:17], v[16:17], v[18:19]
	v_pk_mul_f32 v[14:15], v[14:15], v[94:95]
	v_pk_mul_f32 v[10:11], v[10:11], v[18:19]
	s_and_b64 vcc, exec, s[4:5]
	v_pk_mul_f32 v[8:9], v[8:9], v[94:95]
	s_cbranch_vccnz .LBB0_552
	s_waitcnt vmcnt(8)
	v_pk_mul_f32 v[26:27], v[10:11], v[228:229]
	v_pk_mul_f32 v[28:29], v[8:9], v[226:227]
	v_pk_mul_f32 v[228:229], v[16:17], v[228:229]
	v_pk_mul_f32 v[226:227], v[14:15], v[226:227]
	v_pk_fma_f32 v[16:17], v[16:17], v[232:233], v[26:27] neg_lo:[0,0,1] neg_hi:[0,0,1]
	v_pk_fma_f32 v[14:15], v[14:15], v[230:231], v[28:29] neg_lo:[0,0,1] neg_hi:[0,0,1]
	v_pk_fma_f32 v[10:11], v[10:11], v[232:233], v[228:229]
	v_pk_fma_f32 v[8:9], v[8:9], v[230:231], v[226:227]
.LBB0_552:
	s_nop 0
	v_cvt_pk_bf16_f32 v8, v8, v9
	v_cvt_pk_bf16_f32 v9, v10, v11
	v_mov_b32_e32 v75, v74
	global_store_dwordx2 v[88:89], v[8:9], off offset:288
	v_mov_b32_e32 v8, v74
	v_mov_b32_e32 v9, v74
	v_cvt_pk_bf16_f32 v14, v14, v15
	v_cvt_pk_bf16_f32 v15, v16, v17
	v_pk_mul_f32 v[6:7], v[6:7], v[8:9]
	v_pk_mul_f32 v[4:5], v[4:5], v[74:75]
	v_pk_mul_f32 v[2:3], v[2:3], v[8:9]
	s_and_b64 vcc, exec, s[4:5]
	v_pk_mul_f32 v[0:1], v[0:1], v[74:75]
	global_store_dwordx2 v[88:89], v[14:15], off offset:256
	s_cbranch_vccnz .LBB0_554
	s_waitcnt vmcnt(6)
	v_pk_mul_f32 v[18:19], v[2:3], v[236:237]
	v_pk_mul_f32 v[20:21], v[0:1], v[234:235]
	v_pk_mul_f32 v[236:237], v[6:7], v[236:237]
	v_pk_mul_f32 v[234:235], v[4:5], v[234:235]
	v_pk_fma_f32 v[6:7], v[6:7], v[240:241], v[18:19] neg_lo:[0,0,1] neg_hi:[0,0,1]
	v_pk_fma_f32 v[4:5], v[4:5], v[238:239], v[20:21] neg_lo:[0,0,1] neg_hi:[0,0,1]
	v_pk_fma_f32 v[2:3], v[2:3], v[240:241], v[236:237]
	v_pk_fma_f32 v[0:1], v[0:1], v[238:239], v[234:235]
